# grid barrier: XCD leaders poll the cross-XCD arrival counter directly (one hop less), plus leader-post-before-inv
# speedup vs baseline: 1.0048x; 1.0040x over previous
.LBB0_261:
	s_or_b64 exec, exec, s[8:9]
	v_cvt_f32_u32_e32 v3, v0
	s_waitcnt vmcnt(0)
	v_readfirstlane_b32 s6, v2
	s_add_u32 s8, s82, 0x983500
	s_addc_u32 s9, s83, 0
	v_rcp_iflag_f32_e32 v3, v3
	v_add_u32_e32 v1, s6, v1
	v_add_u32_e32 v4, 1, v1
	s_mov_b64 s[10:11], -1
	v_mul_f32_e32 v2, 0x4f7ffffe, v3
	v_cvt_u32_f32_e32 v2, v2
	v_sub_u32_e32 v3, 0, v0
	v_mul_lo_u32 v3, v3, v2
	v_mul_hi_u32 v3, v2, v3
	v_add_u32_e32 v2, v2, v3
	v_mul_hi_u32 v2, v1, v2
	v_mul_lo_u32 v3, v2, v0
	v_sub_u32_e32 v1, v1, v3
	v_add_u32_e32 v5, 1, v2
	v_cmp_ge_u32_e32 vcc, v1, v0
	v_sub_u32_e32 v3, v1, v0
	s_nop 0
	v_cndmask_b32_e32 v2, v2, v5, vcc
	v_cndmask_b32_e32 v1, v1, v3, vcc
	v_add_u32_e32 v3, 1, v2
	v_cmp_ge_u32_e32 vcc, v1, v0
	s_nop 1
	v_cndmask_b32_e32 v2, v2, v3, vcc
	v_mul_lo_u32 v1, v0, v2
	v_add_u32_e32 v0, v1, v0
	v_cmp_ne_u32_e32 vcc, v4, v0
	v_mov_b32_e32 v5, v0
	v_mov_b64_e32 v[0:1], s[8:9]
	s_and_saveexec_b64 s[6:7], vcc
	s_cbranch_execz .LBB0_273
	v_mov_b32_e32 v0, 0
	global_load_dword v1, v0, s[8:9] offset:-256 sc1
	s_mov_b64 s[18:19], 0
	s_waitcnt vmcnt(0)
	v_cmp_lt_u32_e32 vcc, v1, v5
	s_and_saveexec_b64 s[16:17], vcc
	s_cbranch_execz .LBB0_272
	s_add_u32 s10, s82, 0x980200
	s_addc_u32 s11, s83, 0
	s_mov_b32 s28, 1
	s_branch .LBB0_265

.LBB0_267:
	global_load_dword v1, v0, s[8:9] offset:-256 sc1
	s_add_i32 s28, s28, 1
	s_mov_b64 s[22:23], -1
	s_waitcnt vmcnt(0)
	v_cmp_ge_u32_e32 vcc, v1, v5
	s_orn2_b64 s[26:27], vcc, exec
	s_branch .LBB0_264

.LBB0_483:
	s_or_b64 exec, exec, s[8:9]
	v_cvt_f32_u32_e32 v3, v0
	s_waitcnt vmcnt(0)
	v_readfirstlane_b32 s6, v2
	s_add_u32 s8, s82, 0x983500
	s_addc_u32 s9, s83, 0
	v_rcp_iflag_f32_e32 v3, v3
	v_add_u32_e32 v1, s6, v1
	v_add_u32_e32 v4, 1, v1
	s_mov_b64 s[10:11], -1
	v_mul_f32_e32 v2, 0x4f7ffffe, v3
	v_cvt_u32_f32_e32 v2, v2
	v_sub_u32_e32 v3, 0, v0
	v_mul_lo_u32 v3, v3, v2
	v_mul_hi_u32 v3, v2, v3
	v_add_u32_e32 v2, v2, v3
	v_mul_hi_u32 v2, v1, v2
	v_mul_lo_u32 v3, v2, v0
	v_sub_u32_e32 v1, v1, v3
	v_add_u32_e32 v5, 1, v2
	v_cmp_ge_u32_e32 vcc, v1, v0
	v_sub_u32_e32 v3, v1, v0
	s_nop 0
	v_cndmask_b32_e32 v2, v2, v5, vcc
	v_cndmask_b32_e32 v1, v1, v3, vcc
	v_add_u32_e32 v3, 1, v2
	v_cmp_ge_u32_e32 vcc, v1, v0
	s_nop 1
	v_cndmask_b32_e32 v2, v2, v3, vcc
	v_mul_lo_u32 v1, v0, v2
	v_add_u32_e32 v0, v1, v0
	v_cmp_ne_u32_e32 vcc, v4, v0
	v_mov_b32_e32 v5, v0
	v_mov_b64_e32 v[0:1], s[8:9]
	s_and_saveexec_b64 s[6:7], vcc
	s_cbranch_execz .LBB0_495
	v_mov_b32_e32 v0, 0
	global_load_dword v1, v0, s[8:9] offset:-256 sc1
	s_mov_b64 s[20:21], 0
	s_waitcnt vmcnt(0)
	v_cmp_lt_u32_e32 vcc, v1, v5
	s_and_saveexec_b64 s[18:19], vcc
	s_cbranch_execz .LBB0_494
	s_add_u32 s10, s82, 0x980200
	s_addc_u32 s11, s83, 0
	s_mov_b32 s30, 1
	s_branch .LBB0_487

.LBB0_489:
	global_load_dword v1, v0, s[8:9] offset:-256 sc1
	s_add_i32 s30, s30, 1
	s_mov_b64 s[24:25], -1
	s_waitcnt vmcnt(0)
	v_cmp_ge_u32_e32 vcc, v1, v5
	s_orn2_b64 s[28:29], vcc, exec
	s_branch .LBB0_486

.LBB0_650:
	s_or_b64 exec, exec, s[8:9]
	v_cvt_f32_u32_e32 v3, v0
	s_waitcnt vmcnt(0)
	v_readfirstlane_b32 s6, v2
	s_add_u32 s8, s82, 0x983500
	s_addc_u32 s9, s83, 0
	v_rcp_iflag_f32_e32 v3, v3
	v_add_u32_e32 v1, s6, v1
	v_add_u32_e32 v4, 1, v1
	s_mov_b64 s[10:11], -1
	v_mul_f32_e32 v2, 0x4f7ffffe, v3
	v_cvt_u32_f32_e32 v2, v2
	v_sub_u32_e32 v3, 0, v0
	v_mul_lo_u32 v3, v3, v2
	v_mul_hi_u32 v3, v2, v3
	v_add_u32_e32 v2, v2, v3
	v_mul_hi_u32 v2, v1, v2
	v_mul_lo_u32 v3, v2, v0
	v_sub_u32_e32 v1, v1, v3
	v_add_u32_e32 v5, 1, v2
	v_cmp_ge_u32_e32 vcc, v1, v0
	v_sub_u32_e32 v3, v1, v0
	s_nop 0
	v_cndmask_b32_e32 v2, v2, v5, vcc
	v_cndmask_b32_e32 v1, v1, v3, vcc
	v_add_u32_e32 v3, 1, v2
	v_cmp_ge_u32_e32 vcc, v1, v0
	s_nop 1
	v_cndmask_b32_e32 v2, v2, v3, vcc
	v_mul_lo_u32 v1, v0, v2
	v_add_u32_e32 v0, v1, v0
	v_cmp_ne_u32_e32 vcc, v4, v0
	v_mov_b32_e32 v5, v0
	v_mov_b64_e32 v[0:1], s[8:9]
	s_and_saveexec_b64 s[6:7], vcc
	s_cbranch_execz .LBB0_662
	v_mov_b32_e32 v0, 0
	global_load_dword v1, v0, s[8:9] offset:-256 sc1
	s_mov_b64 s[14:15], 0
	s_waitcnt vmcnt(0)
	v_cmp_lt_u32_e32 vcc, v1, v5
	s_and_saveexec_b64 s[12:13], vcc
	s_cbranch_execz .LBB0_661
	s_add_u32 s10, s82, 0x980200
	s_addc_u32 s11, s83, 0
	s_mov_b32 s24, 1
	s_branch .LBB0_654

.LBB0_656:
	global_load_dword v1, v0, s[8:9] offset:-256 sc1
	s_add_i32 s24, s24, 1
	s_mov_b64 s[18:19], -1
	s_waitcnt vmcnt(0)
	v_cmp_ge_u32_e32 vcc, v1, v5
	s_orn2_b64 s[22:23], vcc, exec
	s_branch .LBB0_653

.LBB0_831:
	s_or_b64 exec, exec, s[6:7]
	v_cvt_f32_u32_e32 v3, v0
	s_waitcnt vmcnt(0)
	v_readfirstlane_b32 s4, v2
	s_add_u32 s6, s70, 0x983500
	s_addc_u32 s7, s71, 0
	v_rcp_iflag_f32_e32 v3, v3
	v_add_u32_e32 v1, s4, v1
	v_add_u32_e32 v4, 1, v1
	s_mov_b64 s[8:9], -1
	v_mul_f32_e32 v2, 0x4f7ffffe, v3
	v_cvt_u32_f32_e32 v2, v2
	v_sub_u32_e32 v3, 0, v0
	v_mul_lo_u32 v3, v3, v2
	v_mul_hi_u32 v3, v2, v3
	v_add_u32_e32 v2, v2, v3
	v_mul_hi_u32 v2, v1, v2
	v_mul_lo_u32 v3, v2, v0
	v_sub_u32_e32 v1, v1, v3
	v_add_u32_e32 v5, 1, v2
	v_cmp_ge_u32_e32 vcc, v1, v0
	v_sub_u32_e32 v3, v1, v0
	s_nop 0
	v_cndmask_b32_e32 v2, v2, v5, vcc
	v_cndmask_b32_e32 v1, v1, v3, vcc
	v_add_u32_e32 v3, 1, v2
	v_cmp_ge_u32_e32 vcc, v1, v0
	s_nop 1
	v_cndmask_b32_e32 v2, v2, v3, vcc
	v_mul_lo_u32 v1, v0, v2
	v_add_u32_e32 v0, v1, v0
	v_cmp_ne_u32_e32 vcc, v4, v0
	v_mov_b32_e32 v5, v0
	v_mov_b64_e32 v[0:1], s[6:7]
	s_and_saveexec_b64 s[4:5], vcc
	s_cbranch_execz .LBB0_843
	v_mov_b32_e32 v0, 0
	global_load_dword v1, v0, s[6:7] offset:-256 sc1
	s_mov_b64 s[12:13], 0
	s_waitcnt vmcnt(0)
	v_cmp_lt_u32_e32 vcc, v1, v5
	s_and_saveexec_b64 s[10:11], vcc
	s_cbranch_execz .LBB0_842
	s_add_u32 s8, s70, 0x980200
	s_addc_u32 s9, s71, 0
	s_mov_b32 s22, 1
	s_branch .LBB0_835

.LBB0_837:
	global_load_dword v1, v0, s[6:7] offset:-256 sc1
	s_add_i32 s22, s22, 1
	s_mov_b64 s[16:17], -1
	s_waitcnt vmcnt(0)
	v_cmp_ge_u32_e32 vcc, v1, v5
	s_orn2_b64 s[20:21], vcc, exec
	s_branch .LBB0_834

.LBB0_971:
	s_or_b64 exec, exec, s[10:11]
	v_cvt_f32_u32_e32 v3, v0
	s_waitcnt vmcnt(0)
	v_readfirstlane_b32 s8, v2
	s_add_u32 s10, s70, 0x983500
	s_addc_u32 s11, s71, 0
	v_rcp_iflag_f32_e32 v3, v3
	v_add_u32_e32 v1, s8, v1
	v_add_u32_e32 v4, 1, v1
	s_mov_b64 s[12:13], -1
	v_mul_f32_e32 v2, 0x4f7ffffe, v3
	v_cvt_u32_f32_e32 v2, v2
	v_sub_u32_e32 v3, 0, v0
	v_mul_lo_u32 v3, v3, v2
	v_mul_hi_u32 v3, v2, v3
	v_add_u32_e32 v2, v2, v3
	v_mul_hi_u32 v2, v1, v2
	v_mul_lo_u32 v3, v2, v0
	v_sub_u32_e32 v1, v1, v3
	v_add_u32_e32 v5, 1, v2
	v_cmp_ge_u32_e32 vcc, v1, v0
	v_sub_u32_e32 v3, v1, v0
	s_nop 0
	v_cndmask_b32_e32 v2, v2, v5, vcc
	v_cndmask_b32_e32 v1, v1, v3, vcc
	v_add_u32_e32 v3, 1, v2
	v_cmp_ge_u32_e32 vcc, v1, v0
	s_nop 1
	v_cndmask_b32_e32 v2, v2, v3, vcc
	v_mul_lo_u32 v1, v0, v2
	v_add_u32_e32 v0, v1, v0
	v_cmp_ne_u32_e32 vcc, v4, v0
	v_mov_b32_e32 v5, v0
	v_mov_b64_e32 v[0:1], s[10:11]
	s_and_saveexec_b64 s[8:9], vcc
	s_cbranch_execz .LBB0_983
	v_mov_b32_e32 v0, 0
	global_load_dword v1, v0, s[10:11] offset:-256 sc1
	s_mov_b64 s[16:17], 0
	s_waitcnt vmcnt(0)
	v_cmp_lt_u32_e32 vcc, v1, v5
	s_and_saveexec_b64 s[14:15], vcc
	s_cbranch_execz .LBB0_982
	s_add_u32 s12, s70, 0x980200
	s_addc_u32 s13, s71, 0
	s_mov_b32 s26, 1
	s_branch .LBB0_975

.LBB0_977:
	global_load_dword v1, v0, s[10:11] offset:-256 sc1
	s_add_i32 s26, s26, 1
	s_mov_b64 s[20:21], -1
	s_waitcnt vmcnt(0)
	v_cmp_ge_u32_e32 vcc, v1, v5
	s_orn2_b64 s[24:25], vcc, exec
	s_branch .LBB0_974

.LBB0_1076:
	s_or_b64 exec, exec, s[8:9]
	v_cvt_f32_u32_e32 v3, v0
	s_waitcnt vmcnt(0)
	v_readfirstlane_b32 s6, v2
	s_add_u32 s8, s70, 0x983500
	s_addc_u32 s9, s71, 0
	v_rcp_iflag_f32_e32 v3, v3
	v_add_u32_e32 v1, s6, v1
	v_add_u32_e32 v4, 1, v1
	s_mov_b64 s[10:11], -1
	v_mul_f32_e32 v2, 0x4f7ffffe, v3
	v_cvt_u32_f32_e32 v2, v2
	v_sub_u32_e32 v3, 0, v0
	v_mul_lo_u32 v3, v3, v2
	v_mul_hi_u32 v3, v2, v3
	v_add_u32_e32 v2, v2, v3
	v_mul_hi_u32 v2, v1, v2
	v_mul_lo_u32 v3, v2, v0
	v_sub_u32_e32 v1, v1, v3
	v_add_u32_e32 v5, 1, v2
	v_cmp_ge_u32_e32 vcc, v1, v0
	v_sub_u32_e32 v3, v1, v0
	s_nop 0
	v_cndmask_b32_e32 v2, v2, v5, vcc
	v_cndmask_b32_e32 v1, v1, v3, vcc
	v_add_u32_e32 v3, 1, v2
	v_cmp_ge_u32_e32 vcc, v1, v0
	s_nop 1
	v_cndmask_b32_e32 v2, v2, v3, vcc
	v_mul_lo_u32 v1, v0, v2
	v_add_u32_e32 v0, v1, v0
	v_cmp_ne_u32_e32 vcc, v4, v0
	v_mov_b32_e32 v5, v0
	v_mov_b64_e32 v[0:1], s[8:9]
	s_and_saveexec_b64 s[6:7], vcc
	s_cbranch_execz .LBB0_1088
	v_mov_b32_e32 v0, 0
	global_load_dword v1, v0, s[8:9] offset:-256 sc1
	s_mov_b64 s[14:15], 0
	s_waitcnt vmcnt(0)
	v_cmp_lt_u32_e32 vcc, v1, v5
	s_and_saveexec_b64 s[12:13], vcc
	s_cbranch_execz .LBB0_1087
	s_add_u32 s10, s70, 0x980200
	s_addc_u32 s11, s71, 0
	s_mov_b32 s24, 1
	s_branch .LBB0_1080
